# P0 conversion loops start at rotated wave indices so every wave gets 7-8 items (was 6-10) and the bias1 workgroups get 7
# speedup vs baseline: 1.0148x; 1.0087x over previous
; #define LAS __attribute__((address_space(3)))
; __device__ __forceinline__ void p0_item(const float* s0, const float* s1, int nv0, int nv1, int N, bf16* dst, int K, LAS float* scr, int lane, const float* gain  ) {
;     ...
;     for (int i = 0; i < 16; ++i) v[i] = ok ? __builtin_nontemporal_load((const f32x4*)(src + (size_t)(4 * i) * N)) : (f32x4){0.f, 0.f, 0.f, 0.f};
; #pragma unroll
;     for (int i = 0; i < 16; ++i) { const float gk = gain ? gain[4 * i + r] : 1.f; LAS float* d = scr + (4 * i + r) * 65 + 4 * c4; d[0] = v[i].x * gk; d[1] = v[i].y * gk; d[2] = v[i].z * gk; d[3] = v[i].w * gk; }
;     const int c = lane & 7;
; #pragma unroll
;     for (int j = 0; j < 8; ++j) {
;         const int n = (lane >> 3) + 8 * j; const LAS float* s = scr + (8 * c) * 65 + n;
;         u32x4 o; o.x = cvtpk(s[0 * 65], s[1 * 65]); o.y = cvtpk(s[2 * 65], s[3 * 65]); o.z = cvtpk(s[4 * 65], s[5 * 65]); o.w = cvtpk(s[6 * 65], s[7 * 65]);
;         __builtin_nontemporal_store(o, (u32x4*)(dst + (size_t)n * K + 8 * c));
;     }
; __device__ __forceinline__ void p0_matrix(int type  , const float* W0, const float* W1, int K, int Nsrc, int Ndst, bf16* dst, LAS float* scr, int gw, int NGW, int lane, const float* gain) {
;     const int nruns = Ndst >> 6, nitems = (K >> 6) * nruns;
;     for (int it = gw; it < nitems; it += NGW) {
;         const int kb = it / nruns, nb = it - kb * nruns, n0 = nb * 64, k0 = kb * 64;
;         const float* src = W0; int c0 = n0, c1 = n0 + 32, nv0 = 32, nv1 = 32;
;         if (type == 1) { const int tile = n0 >> 8, r = n0 & 255; src = r < 128 ? W0 : W1; c0 = tile * 128 + (r & 127); c1 = c0 + 32; }
;         else if (type == 2) { c0 = win_src_col(n0, nv0); c1 = win_src_col(n0 + 32, nv1); }
;         const float* rowp = src + (size_t)k0 * Nsrc;
;         p0_item(rowp + c0, rowp + c1, nv0, nv1, Nsrc, dst + (size_t)n0 * K + k0, K, scr, lane, gain ? gain + k0 : nullptr);
.LBB0_11:
	s_load_dwordx2 s[2:3], s[0:1], 0xe0
	s_mul_i32 s78, s44, 0xb65a400
	s_mov_b32 s79, s45
	s_waitcnt lgkmcnt(0)
	s_add_u32 s77, s2, s78
	s_addc_u32 s90, s3, 0
	s_and_b64 vcc, exec, s[80:81]
	s_cbranch_vccnz .LBB0_47
	s_andn2_b64 vcc, exec, s[48:49]
	s_cbranch_vccnz .LBB0_47
	s_lshl_b64 s[2:3], s[44:45], 13
	s_add_u32 s91, s14, s2
	s_addc_u32 s92, s15, s3
	s_mul_i32 s93, s44, 0x2b00000
	s_mov_b32 s94, s59
	s_mov_b32 s95, s35
	s_mov_b32 s96, s30
	s_cmpk_lg_i32 s34, 0x800
	s_cbranch_scc1 .Lrot_gu1_skip
	s_add_i32 s96, s30, 0x600
	s_and_b32 s96, s96, 0x7ff
	s_lshl_b32 s94, s96, 6
	s_lshl_b32 s95, s96, 5
.Lrot_gu1_skip:
	s_branch .LBB0_15
.LBB0_14:
	s_waitcnt vmcnt(0)
	v_pk_mul_f32 v[2:3], v[2:3], v[10:11] op_sel_hi:[1,0]
	v_add_u32_e32 v6, 0x1450, v27
	s_ashr_i32 s83, s82, 31
	ds_write2_b32 v6, v2, v3 offset1:1
	v_pk_mul_f32 v[2:3], v[4:5], v[10:11] op_sel_hi:[1,0]
	v_add_u32_e32 v4, 0x1458, v27
	s_lshl_b64 s[2:3], s[82:83], 12
	ds_write2_b32 v4, v2, v3 offset1:1
	v_add_u32_e32 v26, 0x400, v126
	s_add_u32 s8, s77, s2
	ds_read2_b32 v[6:7], v126 offset0:65 offset1:73
	ds_read2_b32 v[8:9], v126 offset1:8
	ds_read2_b32 v[10:11], v126 offset0:130 offset1:138
	ds_read2_b32 v[12:13], v126 offset0:195 offset1:203
	ds_read2_b32 v[14:15], v26 offset0:4 offset1:12
	ds_read2_b32 v[16:17], v26 offset0:69 offset1:77
	ds_read2_b32 v[18:19], v26 offset0:134 offset1:142
	ds_read2_b32 v[20:21], v26 offset0:199 offset1:207
	s_addc_u32 s9, s90, s3
	s_lshl_b64 s[2:3], s[80:81], 1
	s_add_u32 s2, s8, s2
	s_addc_u32 s3, s9, s3
	v_mov_b32_e32 v81, v73
	v_lshl_add_u64 v[22:23], s[2:3], 0, v[80:81]
	v_mov_b32_e32 v83, v73
	s_waitcnt lgkmcnt(6)
	v_cvt_pk_bf16_f32 v2, v8, v6
	s_waitcnt lgkmcnt(4)
	v_cvt_pk_bf16_f32 v3, v10, v12
	s_waitcnt lgkmcnt(2)
	v_cvt_pk_bf16_f32 v4, v14, v16
	s_waitcnt lgkmcnt(0)
	v_cvt_pk_bf16_f32 v5, v18, v20
	v_lshl_add_u64 v[24:25], v[22:23], 0, v[82:83]
	global_store_dwordx4 v[24:25], v[2:5], off nt
	v_mov_b32_e32 v85, v73
	v_mov_b32_e32 v87, v73
	v_cvt_pk_bf16_f32 v2, v9, v7
	v_cvt_pk_bf16_f32 v3, v11, v13
	v_cvt_pk_bf16_f32 v4, v15, v17
	v_cvt_pk_bf16_f32 v5, v19, v21
	ds_read2_b32 v[8:9], v126 offset0:81 offset1:89
	ds_read2_b32 v[10:11], v126 offset0:16 offset1:24
	ds_read2_b32 v[12:13], v126 offset0:146 offset1:154
	ds_read2_b32 v[14:15], v126 offset0:211 offset1:219
	ds_read2_b32 v[16:17], v26 offset0:20 offset1:28
	ds_read2_b32 v[18:19], v26 offset0:85 offset1:93
	ds_read2_b32 v[20:21], v26 offset0:150 offset1:158
	ds_read2_b32 v[24:25], v26 offset0:215 offset1:223
	v_lshl_add_u64 v[6:7], v[22:23], 0, v[84:85]
	global_store_dwordx4 v[6:7], v[2:5], off nt
	v_lshl_add_u64 v[6:7], v[22:23], 0, v[86:87]
	v_mov_b32_e32 v89, v73
	s_waitcnt lgkmcnt(6)
	v_cvt_pk_bf16_f32 v2, v10, v8
	s_waitcnt lgkmcnt(4)
	v_cvt_pk_bf16_f32 v3, v12, v14
	s_waitcnt lgkmcnt(2)
	v_cvt_pk_bf16_f32 v4, v16, v18
	s_waitcnt lgkmcnt(0)
	v_cvt_pk_bf16_f32 v5, v20, v24
	global_store_dwordx4 v[6:7], v[2:5], off nt
	v_lshl_add_u64 v[6:7], v[22:23], 0, v[88:89]
	v_mov_b32_e32 v91, v73
	v_cvt_pk_bf16_f32 v2, v11, v9
	v_cvt_pk_bf16_f32 v3, v13, v15
	v_cvt_pk_bf16_f32 v4, v17, v19
	v_cvt_pk_bf16_f32 v5, v21, v25
	ds_read2_b32 v[8:9], v126 offset0:32 offset1:40
	ds_read2_b32 v[10:11], v126 offset0:97 offset1:105
	ds_read2_b32 v[12:13], v126 offset0:162 offset1:170
	ds_read2_b32 v[14:15], v126 offset0:227 offset1:235
	ds_read2_b32 v[16:17], v26 offset0:36 offset1:44
	ds_read2_b32 v[18:19], v26 offset0:101 offset1:109
	ds_read2_b32 v[20:21], v26 offset0:166 offset1:174
	ds_read2_b32 v[24:25], v26 offset0:231 offset1:239
	global_store_dwordx4 v[6:7], v[2:5], off nt
	v_lshl_add_u64 v[6:7], v[22:23], 0, v[90:91]
	v_mov_b32_e32 v93, v73
	s_waitcnt lgkmcnt(6)
	v_cvt_pk_bf16_f32 v2, v8, v10
	s_waitcnt lgkmcnt(4)
	v_cvt_pk_bf16_f32 v3, v12, v14
	s_waitcnt lgkmcnt(2)
	v_cvt_pk_bf16_f32 v4, v16, v18
	s_waitcnt lgkmcnt(0)
	v_cvt_pk_bf16_f32 v5, v20, v24
	global_store_dwordx4 v[6:7], v[2:5], off nt
	v_lshl_add_u64 v[6:7], v[22:23], 0, v[92:93]
	v_mov_b32_e32 v95, v73
	v_cvt_pk_bf16_f32 v2, v9, v11
	v_cvt_pk_bf16_f32 v3, v13, v15
	v_cvt_pk_bf16_f32 v4, v17, v19
	v_cvt_pk_bf16_f32 v5, v21, v25
	ds_read2_b32 v[8:9], v126 offset0:48 offset1:56
	ds_read2_b32 v[10:11], v126 offset0:113 offset1:121
	ds_read2_b32 v[12:13], v126 offset0:178 offset1:186
	ds_read2_b32 v[14:15], v126 offset0:243 offset1:251
	ds_read2_b32 v[16:17], v26 offset0:52 offset1:60
	ds_read2_b32 v[18:19], v26 offset0:117 offset1:125
	ds_read2_b32 v[20:21], v26 offset0:182 offset1:190
	ds_read2_b32 v[24:25], v26 offset0:247 offset1:255
	v_readlane_b32 s2, v253, 0
	global_store_dwordx4 v[6:7], v[2:5], off nt
	v_lshl_add_u64 v[6:7], v[22:23], 0, v[94:95]
	v_mov_b32_e32 v97, v73
	s_waitcnt lgkmcnt(6)
	v_cvt_pk_bf16_f32 v2, v8, v10
	s_waitcnt lgkmcnt(4)
	v_cvt_pk_bf16_f32 v3, v12, v14
	s_waitcnt lgkmcnt(2)
	v_cvt_pk_bf16_f32 v4, v16, v18
	s_waitcnt lgkmcnt(0)
	v_cvt_pk_bf16_f32 v5, v20, v24
	s_add_i32 s96, s96, s34
	s_add_i32 s95, s95, s2
	s_add_i32 s94, s94, s76
	global_store_dwordx4 v[6:7], v[2:5], off nt
	v_lshl_add_u64 v[6:7], v[22:23], 0, v[96:97]
	s_cmpk_lt_i32 s96, 0x1580
	v_cvt_pk_bf16_f32 v2, v9, v11
	v_cvt_pk_bf16_f32 v3, v13, v15
	v_cvt_pk_bf16_f32 v4, v17, v19
	v_cvt_pk_bf16_f32 v5, v21, v25
	global_store_dwordx4 v[6:7], v[2:5], off nt
	s_cbranch_scc0 .LBB0_47

; #define LAS __attribute__((address_space(3)))
; __device__ __forceinline__ void p0_item(const float* s0, const float* s1, int nv0, int nv1, int N, bf16* dst, int K, LAS float* scr, int lane, const float* gain  ) {
;     ...
;     f32x4 v[16];
; #pragma unroll
;     for (int i = 0; i < 16; ++i) v[i] = ok ? __builtin_nontemporal_load((const f32x4*)(src + (size_t)(4 * i) * N)) : (f32x4){0.f, 0.f, 0.f, 0.f};
; #pragma unroll
;     for (int i = 0; i < 16; ++i) { const float gk = gain ? gain[4 * i + r] : 1.f; LAS float* d = scr + (4 * i + r) * 65 + 4 * c4; d[0] = v[i].x * gk; d[1] = v[i].y * gk; d[2] = v[i].z * gk; d[3] = v[i].w * gk; }
; __device__ __forceinline__ void p0_matrix(int type  , const float* W0, const float* W1, int K, int Nsrc, int Ndst, bf16* dst, LAS float* scr, int gw, int NGW, int lane, const float* gain) {
;     ...
;     for (int it = gw; it < nitems; it += NGW) {
;         const int kb = it / nruns, nb = it - kb * nruns, n0 = nb * 64, k0 = kb * 64;
;         const float* src = W0; int c0 = n0, c1 = n0 + 32, nv0 = 32, nv1 = 32;
;         if (type == 1) { const int tile = n0 >> 8, r = n0 & 255; src = r < 128 ? W0 : W1; c0 = tile * 128 + (r & 127); c1 = c0 + 32; }
;         else if (type == 2) { c0 = win_src_col(n0, nv0); c1 = win_src_col(n0 + 32, nv1); }
;         const float* rowp = src + (size_t)k0 * Nsrc;
.LBB0_47:
	s_andn2_b64 vcc, exec, s[46:47]
	s_cbranch_vccnz .LBB0_50
	s_mul_i32 s2, s44, 0x2b00000
	s_add_u32 s80, s20, s2
	s_addc_u32 s81, s21, 0
	s_add_u32 s82, s77, 0x2b00000
	s_addc_u32 s83, s90, 0
	s_mov_b32 s86, s59
	s_mov_b32 s87, s30
	s_cmpk_lg_i32 s34, 0x800
	s_cbranch_scc1 .Lrot_d1_skip
	s_mul_i32 s2, s44, 0x3c0
	s_add_i32 s87, s30, s2
	s_addk_i32 s87, 0x80
	s_and_b32 s87, s87, 0x7ff
	s_lshl_b32 s86, s87, 6
.Lrot_d1_skip:
.LBB0_49:
	s_ashr_i32 s2, s87, 31
	s_lshr_b32 s2, s2, 27
	s_add_i32 s2, s87, s2
	s_ashr_i32 s2, s2, 5
	s_lshl_b32 s3, s2, 11
	s_lshl_b32 s2, s2, 6
	s_sub_i32 s91, s86, s3
	s_ashr_i32 s3, s2, 31
	s_lshl_b64 s[8:9], s[2:3], 13
	s_add_u32 s88, s80, s8
	v_add_u32_e32 v2, s91, v131
	s_addc_u32 s89, s81, s9
	s_mul_i32 s9, s91, 0x2b00
	v_ashrrev_i32_e32 v3, 31, v2
	s_mul_hi_i32 s8, s91, 0x2b00
	s_add_u32 s9, s82, s9
	v_lshl_add_u64 v[2:3], v[2:3], 2, s[88:89]
	v_mov_b32_e32 v99, v73
	s_addc_u32 s92, s83, s8
	s_lshl_b64 s[2:3], s[2:3], 1
	v_lshl_add_u64 v[2:3], v[2:3], 0, v[98:99]
	v_mov_b32_e32 v115, v73
	s_add_u32 s8, s9, s2
	v_lshl_add_u64 v[62:63], v[2:3], 0, v[114:115]
	s_mov_b32 s2, 0x8000
	v_add_co_u32_e32 v6, vcc, s2, v62
	global_load_dwordx4 v[2:5], v[62:63], off nt
	s_nop 0
	v_addc_co_u32_e32 v7, vcc, 0, v63, vcc
	s_mov_b32 s2, 0x10000
	global_load_dwordx4 v[6:9], v[6:7], off nt
	v_add_co_u32_e32 v10, vcc, s2, v62
	s_mov_b32 s2, 0x18000
	s_nop 0
	v_addc_co_u32_e32 v11, vcc, 0, v63, vcc
	global_load_dwordx4 v[10:13], v[10:11], off nt
	v_add_co_u32_e32 v14, vcc, s2, v62
	s_mov_b32 s2, 0x28000
	s_nop 0
	v_addc_co_u32_e32 v15, vcc, 0, v63, vcc
	global_load_dwordx4 v[18:21], v[14:15], off nt
	v_add_co_u32_e32 v14, vcc, s31, v62
	v_add_u32_e32 v81, v67, v130
	s_nop 0
	v_addc_co_u32_e32 v15, vcc, 0, v63, vcc
	global_load_dwordx4 v[14:17], v[14:15], off nt
	v_add_co_u32_e32 v22, vcc, s2, v62
	s_mov_b32 s2, 0x30000
	s_nop 0
	v_addc_co_u32_e32 v23, vcc, 0, v63, vcc
	global_load_dwordx4 v[22:25], v[22:23], off nt
	v_add_co_u32_e32 v26, vcc, s2, v62
	s_mov_b32 s2, 0x38000
	s_nop 0
	v_addc_co_u32_e32 v27, vcc, 0, v63, vcc
	global_load_dwordx4 v[26:29], v[26:27], off nt
	v_add_co_u32_e32 v30, vcc, s2, v62
	s_mov_b32 s2, 0x48000
	s_nop 0
	v_addc_co_u32_e32 v31, vcc, 0, v63, vcc
	global_load_dwordx4 v[34:37], v[30:31], off nt
	v_add_co_u32_e32 v30, vcc, s85, v62
	s_addc_u32 s9, s92, s3
	s_nop 0
	v_addc_co_u32_e32 v31, vcc, 0, v63, vcc
	global_load_dwordx4 v[30:33], v[30:31], off nt
	v_add_co_u32_e32 v38, vcc, s2, v62
	s_mov_b32 s2, 0x50000
	s_nop 0
	v_addc_co_u32_e32 v39, vcc, 0, v63, vcc
	global_load_dwordx4 v[38:41], v[38:39], off nt
	v_add_co_u32_e32 v42, vcc, s2, v62
	s_mov_b32 s2, 0x58000
	s_nop 0
	v_addc_co_u32_e32 v43, vcc, 0, v63, vcc
	global_load_dwordx4 v[42:45], v[42:43], off nt
	v_add_co_u32_e32 v46, vcc, s2, v62
	s_mov_b32 s2, 0x60000
	s_nop 0
	v_addc_co_u32_e32 v47, vcc, 0, v63, vcc
	global_load_dwordx4 v[46:49], v[46:47], off nt
	v_add_co_u32_e32 v50, vcc, s2, v62
	s_mov_b32 s2, 0x68000
	s_nop 0
	v_addc_co_u32_e32 v51, vcc, 0, v63, vcc
	global_load_dwordx4 v[50:53], v[50:51], off nt
	v_add_co_u32_e32 v54, vcc, s2, v62
	s_mov_b32 s2, 0x70000
	s_nop 0
	v_addc_co_u32_e32 v55, vcc, 0, v63, vcc
	global_load_dwordx4 v[54:57], v[54:55], off nt
	v_add_co_u32_e32 v58, vcc, s2, v62
	s_mov_b32 s2, 0x78000
	s_nop 0
	v_addc_co_u32_e32 v59, vcc, 0, v63, vcc
	global_load_dwordx4 v[58:61], v[58:59], off nt
	v_add_co_u32_e32 v62, vcc, s2, v62
	v_mov_b32_e32 v101, v73
	s_nop 0
	v_addc_co_u32_e32 v63, vcc, 0, v63, vcc
	global_load_dwordx4 v[62:65], v[62:63], off nt
	s_waitcnt vmcnt(15)
	ds_write2_b32 v81, v2, v3 offset1:1
	ds_write2_b32 v81, v4, v5 offset0:2 offset1:3
	v_add_u32_e32 v2, 0x410, v81
	s_waitcnt vmcnt(14)
	ds_write2_b32 v2, v6, v7 offset1:1
	v_add_u32_e32 v2, 0x418, v81
	ds_write2_b32 v2, v8, v9 offset1:1
	v_add_u32_e32 v2, 0x820, v81
	s_waitcnt vmcnt(13)
	ds_write2_b32 v2, v10, v11 offset1:1
	v_add_u32_e32 v2, 0x828, v81
	ds_write2_b32 v2, v12, v13 offset1:1
	v_add_u32_e32 v2, 0xc30, v81
	s_waitcnt vmcnt(12)
	ds_write2_b32 v2, v18, v19 offset1:1
	v_add_u32_e32 v2, 0xc38, v81
	ds_write2_b32 v2, v20, v21 offset1:1
	v_add_u32_e32 v2, 0x1040, v81
	s_waitcnt vmcnt(11)
	ds_write2_b32 v2, v14, v15 offset1:1
	v_add_u32_e32 v2, 0x1048, v81
	ds_write2_b32 v2, v16, v17 offset1:1
	v_add_u32_e32 v2, 0x1450, v81
	v_mov_b32_e32 v103, v73
	s_waitcnt vmcnt(10)
	ds_write2_b32 v2, v22, v23 offset1:1
	v_add_u32_e32 v2, 0x1458, v81
	ds_write2_b32 v2, v24, v25 offset1:1
	v_add_u32_e32 v2, 0x1860, v81
	v_mov_b32_e32 v105, v73
	v_mov_b32_e32 v107, v73
	s_waitcnt vmcnt(9)
	ds_write2_b32 v2, v26, v27 offset1:1
	v_add_u32_e32 v2, 0x1868, v81
	ds_write2_b32 v2, v28, v29 offset1:1
	v_add_u32_e32 v2, 0x1c70, v81
	v_add_u32_e32 v28, 0x400, v126
	v_mov_b32_e32 v109, v73
	s_waitcnt vmcnt(8)
	ds_write2_b32 v2, v34, v35 offset1:1
	v_add_u32_e32 v2, 0x1c78, v81
	ds_write2_b32 v2, v36, v37 offset1:1
	v_add_u32_e32 v2, 0x2080, v81
	s_add_i32 s87, s87, s34
	s_add_i32 s86, s86, s76
	s_waitcnt vmcnt(7)
	ds_write2_b32 v2, v30, v31 offset1:1
	v_add_u32_e32 v2, 0x2088, v81
	ds_write2_b32 v2, v32, v33 offset1:1
	v_add_u32_e32 v2, 0x2490, v81
	s_cmpk_lt_i32 s87, 0xac0
	s_waitcnt vmcnt(6)
	ds_write2_b32 v2, v38, v39 offset1:1
	v_add_u32_e32 v2, 0x2498, v81
	ds_write2_b32 v2, v40, v41 offset1:1
	v_add_u32_e32 v2, 0x28a0, v81
	s_waitcnt vmcnt(5)
	ds_write2_b32 v2, v42, v43 offset1:1
	v_add_u32_e32 v2, 0x28a8, v81
	ds_write2_b32 v2, v44, v45 offset1:1
	v_add_u32_e32 v2, 0x2cb0, v81
	s_waitcnt vmcnt(4)
	ds_write2_b32 v2, v46, v47 offset1:1
	v_add_u32_e32 v2, 0x2cb8, v81
	ds_write2_b32 v2, v48, v49 offset1:1
	v_add_u32_e32 v2, 0x30c0, v81
	s_waitcnt vmcnt(3)
; #define LAS __attribute__((address_space(3)))
; __device__ __forceinline__ void p0_item(const float* s0, const float* s1, int nv0, int nv1, int N, bf16* dst, int K, LAS float* scr, int lane, const float* gain  ) {
;     ...
;     for (int i = 0; i < 16; ++i) { const float gk = gain ? gain[4 * i + r] : 1.f; LAS float* d = scr + (4 * i + r) * 65 + 4 * c4; d[0] = v[i].x * gk; d[1] = v[i].y * gk; d[2] = v[i].z * gk; d[3] = v[i].w * gk; }
;     const int c = lane & 7;
; #pragma unroll
;     for (int j = 0; j < 8; ++j) {
;         const int n = (lane >> 3) + 8 * j; const LAS float* s = scr + (8 * c) * 65 + n;
;         u32x4 o; o.x = cvtpk(s[0 * 65], s[1 * 65]); o.y = cvtpk(s[2 * 65], s[3 * 65]); o.z = cvtpk(s[4 * 65], s[5 * 65]); o.w = cvtpk(s[6 * 65], s[7 * 65]);
;         __builtin_nontemporal_store(o, (u32x4*)(dst + (size_t)n * K + 8 * c));
;     }
; __device__ __forceinline__ void conv_set(const CvPtrs args, unsigned char* ws, int l, unsigned mask, LAS float* scr, int gw, int NGW, int lane) {
;     unsigned char* lw = ws + (size_t)l * LW_BYTES;
;     if (mask & CV_GU1) p0_matrix(1, args.in[3] + (size_t)l * D * FF, args.in[4] + (size_t)l * D * FF, D, FF, 2 * FF, (bf16*)(lw + LW_GU1), scr, gw, NGW, lane, args.in[2] + (size_t)l * D);
;     if (mask & CV_D1) p0_matrix(0, args.in[5] + (size_t)l * FF * D, nullptr, FF, D, D, (bf16*)(lw + LW_D1), scr, gw, NGW, lane, nullptr);
;     if (mask & CV_WIN) p0_matrix(2, args.in[7] + (size_t)l * D * INW, nullptr, D, INW, INP, (bf16*)(lw + LW_IN), scr, gw, NGW, lane, args.in[6] + (size_t)l * D);
	ds_write2_b32 v2, v50, v51 offset1:1
	v_add_u32_e32 v2, 0x30c8, v81
	ds_write2_b32 v2, v52, v53 offset1:1
	v_add_u32_e32 v2, 0x34d0, v81
	s_waitcnt vmcnt(2)
	ds_write2_b32 v2, v54, v55 offset1:1
	v_add_u32_e32 v2, 0x34d8, v81
	ds_write2_b32 v2, v56, v57 offset1:1
	v_add_u32_e32 v2, 0x38e0, v81
	s_waitcnt vmcnt(1)
	ds_write2_b32 v2, v58, v59 offset1:1
	v_add_u32_e32 v2, 0x38e8, v81
	ds_write2_b32 v2, v60, v61 offset1:1
	v_add_u32_e32 v2, 0x3cf0, v81
	s_waitcnt vmcnt(0)
	ds_write2_b32 v2, v62, v63 offset1:1
	v_add_u32_e32 v2, 0x3cf8, v81
	ds_write2_b32 v2, v64, v65 offset1:1
	ds_read2_b32 v[8:9], v126 offset0:65 offset1:73
	ds_read2_b32 v[10:11], v126 offset1:8
	ds_read2_b32 v[12:13], v126 offset0:130 offset1:138
	ds_read2_b32 v[14:15], v126 offset0:195 offset1:203
	ds_read2_b32 v[16:17], v28 offset0:4 offset1:12
	ds_read2_b32 v[18:19], v28 offset0:69 offset1:77
	ds_read2_b32 v[20:21], v28 offset0:134 offset1:142
	ds_read2_b32 v[22:23], v28 offset0:199 offset1:207
	v_mov_b32_e32 v81, v73
	v_lshl_add_u64 v[2:3], s[8:9], 0, v[80:81]
	v_lshl_add_u64 v[24:25], v[2:3], 0, v[100:101]
	s_waitcnt lgkmcnt(6)
	v_cvt_pk_bf16_f32 v4, v10, v8
	s_waitcnt lgkmcnt(4)
	v_cvt_pk_bf16_f32 v5, v12, v14
	s_waitcnt lgkmcnt(2)
	v_cvt_pk_bf16_f32 v6, v16, v18
	s_waitcnt lgkmcnt(0)
	v_cvt_pk_bf16_f32 v7, v20, v22
	v_add_co_u32_e32 v8, vcc, s84, v24
	global_store_dwordx4 v[24:25], v[4:7], off nt
	s_nop 1
	v_cvt_pk_bf16_f32 v4, v11, v9
	v_cvt_pk_bf16_f32 v5, v13, v15
	v_cvt_pk_bf16_f32 v6, v17, v19
	v_cvt_pk_bf16_f32 v7, v21, v23
	v_addc_co_u32_e32 v9, vcc, 0, v25, vcc
	global_store_dwordx4 v[8:9], v[4:7], off offset:2048 nt
	ds_read2_b32 v[8:9], v126 offset0:16 offset1:24
	ds_read2_b32 v[10:11], v126 offset0:81 offset1:89
	ds_read2_b32 v[12:13], v126 offset0:146 offset1:154
	ds_read2_b32 v[14:15], v126 offset0:211 offset1:219
	ds_read2_b32 v[16:17], v28 offset0:20 offset1:28
	ds_read2_b32 v[18:19], v28 offset0:85 offset1:93
	ds_read2_b32 v[20:21], v28 offset0:150 offset1:158
	ds_read2_b32 v[22:23], v28 offset0:215 offset1:223
	v_add_co_u32_e32 v26, vcc, s33, v24
	s_waitcnt lgkmcnt(6)
	v_cvt_pk_bf16_f32 v4, v8, v10
	v_addc_co_u32_e32 v27, vcc, 0, v25, vcc
	s_waitcnt lgkmcnt(4)
	v_cvt_pk_bf16_f32 v5, v12, v14
	s_waitcnt lgkmcnt(2)
	v_cvt_pk_bf16_f32 v6, v16, v18
	s_waitcnt lgkmcnt(0)
	v_cvt_pk_bf16_f32 v7, v20, v22
	v_add_co_u32_e32 v8, vcc, s85, v24
	global_store_dwordx4 v[26:27], v[4:7], off nt
	s_nop 1
	v_cvt_pk_bf16_f32 v4, v9, v11
	v_cvt_pk_bf16_f32 v5, v13, v15
	v_cvt_pk_bf16_f32 v6, v17, v19
	v_cvt_pk_bf16_f32 v7, v21, v23
	v_addc_co_u32_e32 v9, vcc, 0, v25, vcc
	global_store_dwordx4 v[8:9], v[4:7], off offset:2048 nt
	ds_read2_b32 v[8:9], v126 offset0:32 offset1:40
	ds_read2_b32 v[10:11], v126 offset0:97 offset1:105
	ds_read2_b32 v[12:13], v126 offset0:162 offset1:170
	ds_read2_b32 v[14:15], v126 offset0:227 offset1:235
	ds_read2_b32 v[16:17], v28 offset0:36 offset1:44
	ds_read2_b32 v[18:19], v28 offset0:101 offset1:109
	ds_read2_b32 v[20:21], v28 offset0:166 offset1:174
	ds_read2_b32 v[22:23], v28 offset0:231 offset1:239
	v_lshl_add_u64 v[24:25], v[2:3], 0, v[102:103]
	s_waitcnt lgkmcnt(6)
	v_cvt_pk_bf16_f32 v4, v8, v10
	s_waitcnt lgkmcnt(4)
	v_cvt_pk_bf16_f32 v5, v12, v14
	s_waitcnt lgkmcnt(2)
	v_cvt_pk_bf16_f32 v6, v16, v18
	s_waitcnt lgkmcnt(0)
	v_cvt_pk_bf16_f32 v7, v20, v22
	global_store_dwordx4 v[24:25], v[4:7], off nt
	v_lshl_add_u64 v[24:25], v[2:3], 0, v[106:107]
	s_nop 0
	v_cvt_pk_bf16_f32 v4, v9, v11
	v_cvt_pk_bf16_f32 v5, v13, v15
	v_cvt_pk_bf16_f32 v6, v17, v19
	v_cvt_pk_bf16_f32 v7, v21, v23
	v_lshl_add_u64 v[8:9], v[2:3], 0, v[104:105]
	global_store_dwordx4 v[8:9], v[4:7], off nt
	ds_read2_b32 v[8:9], v126 offset0:48 offset1:56
	ds_read2_b32 v[10:11], v126 offset0:113 offset1:121
	ds_read2_b32 v[12:13], v126 offset0:178 offset1:186
	ds_read2_b32 v[14:15], v126 offset0:243 offset1:251
	ds_read2_b32 v[16:17], v28 offset0:52 offset1:60
	ds_read2_b32 v[18:19], v28 offset0:117 offset1:125
	ds_read2_b32 v[20:21], v28 offset0:182 offset1:190
	ds_read2_b32 v[22:23], v28 offset0:247 offset1:255
	v_lshl_add_u64 v[2:3], v[2:3], 0, v[108:109]
	s_waitcnt lgkmcnt(6)
	v_cvt_pk_bf16_f32 v4, v8, v10
	s_waitcnt lgkmcnt(4)
	v_cvt_pk_bf16_f32 v5, v12, v14
	s_waitcnt lgkmcnt(2)
	v_cvt_pk_bf16_f32 v6, v16, v18
	s_waitcnt lgkmcnt(0)
	v_cvt_pk_bf16_f32 v7, v20, v22
	global_store_dwordx4 v[24:25], v[4:7], off nt
	s_nop 1
	v_cvt_pk_bf16_f32 v4, v9, v11
	v_cvt_pk_bf16_f32 v5, v13, v15
	v_cvt_pk_bf16_f32 v6, v17, v19
	v_cvt_pk_bf16_f32 v7, v21, v23
	global_store_dwordx4 v[2:3], v[4:7], off nt
	s_cbranch_scc1 .LBB0_49
.LBB0_50:
	s_andn2_b64 vcc, exec, s[74:75]
	s_cbranch_vccnz .LBB0_150
	s_andn2_b64 vcc, exec, s[52:53]
	s_cbranch_vccnz .LBB0_150
	s_mul_i32 s2, s44, 0x4460000
	s_add_u32 s91, s24, s2
	s_addc_u32 s92, s25, 0
	s_add_u32 s77, s77, 0x4080000
	s_addc_u32 s90, s90, 0
	s_mov_b32 s93, s59
	s_mov_b32 s94, s30
	s_cmpk_lg_i32 s34, 0x800
	s_cbranch_scc1 .Lrot_win_skip
	s_add_i32 s94, s30, 0x5c0
	s_and_b32 s94, s94, 0x7ff
	s_lshl_b32 s93, s94, 6
; #define LAS __attribute__((address_space(3)))
; __device__ __forceinline__ void p0_item(const float* s0, const float* s1, int nv0, int nv1, int N, bf16* dst, int K, LAS float* scr, int lane, const float* gain  ) {
;     ...
;     for (int i = 0; i < 16; ++i) { const float gk = gain ? gain[4 * i + r] : 1.f; LAS float* d = scr + (4 * i + r) * 65 + 4 * c4; d[0] = v[i].x * gk; d[1] = v[i].y * gk; d[2] = v[i].z * gk; d[3] = v[i].w * gk; }
;     const int c = lane & 7;
; #pragma unroll
;     for (int j = 0; j < 8; ++j) {
;         const int n = (lane >> 3) + 8 * j; const LAS float* s = scr + (8 * c) * 65 + n;
;         u32x4 o; o.x = cvtpk(s[0 * 65], s[1 * 65]); o.y = cvtpk(s[2 * 65], s[3 * 65]); o.z = cvtpk(s[4 * 65], s[5 * 65]); o.w = cvtpk(s[6 * 65], s[7 * 65]);
;         __builtin_nontemporal_store(o, (u32x4*)(dst + (size_t)n * K + 8 * c));
;     }
; __device__ __forceinline__ void p0_matrix(int type  , const float* W0, const float* W1, int K, int Nsrc, int Ndst, bf16* dst, LAS float* scr, int gw, int NGW, int lane, const float* gain) {
;     ...
;     for (int it = gw; it < nitems; it += NGW) {
;         const int kb = it / nruns, nb = it - kb * nruns, n0 = nb * 64, k0 = kb * 64;
.Lrot_win_skip:
	s_branch .LBB0_54
.LBB0_53:
	s_waitcnt vmcnt(0)
	v_pk_mul_f32 v[4:5], v[54:55], v[2:3] op_sel_hi:[1,0]
	v_add_u32_e32 v6, 0x1450, v3
	s_ashr_i32 s81, s80, 31
	ds_write2_b32 v6, v4, v5 offset1:1
	v_pk_mul_f32 v[4:5], v[56:57], v[2:3] op_sel_hi:[1,0]
	v_add_u32_e32 v2, 0x1458, v3
	s_lshl_b64 s[2:3], s[80:81], 12
	ds_write2_b32 v2, v4, v5 offset1:1
	v_add_u32_e32 v26, 0x400, v126
	s_add_u32 s8, s77, s2
	ds_read2_b32 v[6:7], v126 offset0:65 offset1:73
	ds_read2_b32 v[8:9], v126 offset1:8
	ds_read2_b32 v[10:11], v126 offset0:130 offset1:138
	ds_read2_b32 v[12:13], v126 offset0:195 offset1:203
	ds_read2_b32 v[14:15], v26 offset0:4 offset1:12
	ds_read2_b32 v[16:17], v26 offset0:69 offset1:77
	ds_read2_b32 v[18:19], v26 offset0:134 offset1:142
	ds_read2_b32 v[20:21], v26 offset0:199 offset1:207
	s_addc_u32 s9, s90, s3
	s_lshl_b64 s[2:3], s[82:83], 1
	s_add_u32 s2, s8, s2
	s_addc_u32 s3, s9, s3
	v_mov_b32_e32 v81, v73
	v_lshl_add_u64 v[22:23], s[2:3], 0, v[80:81]
	v_mov_b32_e32 v83, v73
	s_waitcnt lgkmcnt(6)
	v_cvt_pk_bf16_f32 v2, v8, v6
	s_waitcnt lgkmcnt(4)
	v_cvt_pk_bf16_f32 v3, v10, v12
	s_waitcnt lgkmcnt(2)
	v_cvt_pk_bf16_f32 v4, v14, v16
	s_waitcnt lgkmcnt(0)
	v_cvt_pk_bf16_f32 v5, v18, v20
	v_lshl_add_u64 v[24:25], v[22:23], 0, v[82:83]
	global_store_dwordx4 v[24:25], v[2:5], off nt
	v_mov_b32_e32 v85, v73
	v_mov_b32_e32 v87, v73
	v_cvt_pk_bf16_f32 v2, v9, v7
	v_cvt_pk_bf16_f32 v3, v11, v13
	v_cvt_pk_bf16_f32 v4, v15, v17
	v_cvt_pk_bf16_f32 v5, v19, v21
	ds_read2_b32 v[8:9], v126 offset0:81 offset1:89
	ds_read2_b32 v[10:11], v126 offset0:16 offset1:24
	ds_read2_b32 v[12:13], v126 offset0:146 offset1:154
	ds_read2_b32 v[14:15], v126 offset0:211 offset1:219
	ds_read2_b32 v[16:17], v26 offset0:20 offset1:28
	ds_read2_b32 v[18:19], v26 offset0:85 offset1:93
	ds_read2_b32 v[20:21], v26 offset0:150 offset1:158
	ds_read2_b32 v[24:25], v26 offset0:215 offset1:223
	v_lshl_add_u64 v[6:7], v[22:23], 0, v[84:85]
	global_store_dwordx4 v[6:7], v[2:5], off nt
	v_lshl_add_u64 v[6:7], v[22:23], 0, v[86:87]
	v_mov_b32_e32 v89, v73
	s_waitcnt lgkmcnt(6)
	v_cvt_pk_bf16_f32 v2, v10, v8
	s_waitcnt lgkmcnt(4)
	v_cvt_pk_bf16_f32 v3, v12, v14
	s_waitcnt lgkmcnt(2)
	v_cvt_pk_bf16_f32 v4, v16, v18
	s_waitcnt lgkmcnt(0)
	v_cvt_pk_bf16_f32 v5, v20, v24
	global_store_dwordx4 v[6:7], v[2:5], off nt
	v_lshl_add_u64 v[6:7], v[22:23], 0, v[88:89]
	v_mov_b32_e32 v91, v73
	v_cvt_pk_bf16_f32 v2, v11, v9
	v_cvt_pk_bf16_f32 v3, v13, v15
	v_cvt_pk_bf16_f32 v4, v17, v19
	v_cvt_pk_bf16_f32 v5, v21, v25
	ds_read2_b32 v[8:9], v126 offset0:32 offset1:40
	ds_read2_b32 v[10:11], v126 offset0:97 offset1:105
	ds_read2_b32 v[12:13], v126 offset0:162 offset1:170
	ds_read2_b32 v[14:15], v126 offset0:227 offset1:235
	ds_read2_b32 v[16:17], v26 offset0:36 offset1:44
	ds_read2_b32 v[18:19], v26 offset0:101 offset1:109
	ds_read2_b32 v[20:21], v26 offset0:166 offset1:174
	ds_read2_b32 v[24:25], v26 offset0:231 offset1:239
	global_store_dwordx4 v[6:7], v[2:5], off nt
	v_lshl_add_u64 v[6:7], v[22:23], 0, v[90:91]
	v_mov_b32_e32 v93, v73
	s_waitcnt lgkmcnt(6)
	v_cvt_pk_bf16_f32 v2, v8, v10
	s_waitcnt lgkmcnt(4)
	v_cvt_pk_bf16_f32 v3, v12, v14
	s_waitcnt lgkmcnt(2)
	v_cvt_pk_bf16_f32 v4, v16, v18
	s_waitcnt lgkmcnt(0)
	v_cvt_pk_bf16_f32 v5, v20, v24
	global_store_dwordx4 v[6:7], v[2:5], off nt
	v_lshl_add_u64 v[6:7], v[22:23], 0, v[92:93]
	v_mov_b32_e32 v95, v73
	v_cvt_pk_bf16_f32 v2, v9, v11
	v_cvt_pk_bf16_f32 v3, v13, v15
	v_cvt_pk_bf16_f32 v4, v17, v19
	v_cvt_pk_bf16_f32 v5, v21, v25
	ds_read2_b32 v[8:9], v126 offset0:48 offset1:56
	ds_read2_b32 v[10:11], v126 offset0:113 offset1:121
	ds_read2_b32 v[12:13], v126 offset0:178 offset1:186
	ds_read2_b32 v[14:15], v126 offset0:243 offset1:251
	ds_read2_b32 v[16:17], v26 offset0:52 offset1:60
	ds_read2_b32 v[18:19], v26 offset0:117 offset1:125
	ds_read2_b32 v[20:21], v26 offset0:182 offset1:190
	ds_read2_b32 v[24:25], v26 offset0:247 offset1:255
	global_store_dwordx4 v[6:7], v[2:5], off nt
	v_lshl_add_u64 v[6:7], v[22:23], 0, v[94:95]
	v_mov_b32_e32 v97, v73
	s_waitcnt lgkmcnt(6)
	v_cvt_pk_bf16_f32 v2, v8, v10
	s_waitcnt lgkmcnt(4)
	v_cvt_pk_bf16_f32 v3, v12, v14
	s_waitcnt lgkmcnt(2)
	v_cvt_pk_bf16_f32 v4, v16, v18
	s_waitcnt lgkmcnt(0)
	v_cvt_pk_bf16_f32 v5, v20, v24
	s_add_i32 s94, s94, s34
	s_add_i32 s93, s93, s76
	global_store_dwordx4 v[6:7], v[2:5], off nt
	v_lshl_add_u64 v[6:7], v[22:23], 0, v[96:97]
	s_cmpk_lt_i32 s94, 0x1180
	v_cvt_pk_bf16_f32 v2, v9, v11
	v_cvt_pk_bf16_f32 v3, v13, v15
	v_cvt_pk_bf16_f32 v4, v17, v19
	v_cvt_pk_bf16_f32 v5, v21, v25
	global_store_dwordx4 v[6:7], v[2:5], off nt
	s_cbranch_scc0 .LBB0_150
